# stack + multi-tile GEMMs (w_in, w1): first K-step waits of a unit relaxed by the previous unit's 16 epilogue stores
# baseline (speedup 1.0000x reference)
.LBB0_494:
	v_add_u32_e32 v138, 0x10000, v229
	v_add_u32_e32 v150, 0x14000, v229
	ds_read_b128 v[154:157], v138
	ds_read_b128 v[158:161], v138 offset:1024
	ds_read_b128 v[162:165], v138 offset:2048
	ds_read_b128 v[166:169], v138 offset:3072
	ds_read_b128 v[138:141], v150
	ds_read_b128 v[142:145], v150 offset:1024
	ds_read_b128 v[146:149], v150 offset:2048
	ds_read_b128 v[150:153], v150 offset:3072
	s_cmp_lg_u32 s55, s64
	s_cselect_b64 s[28:29], -1, 0
	s_add_u32 s26, s22, 0xfffc0080
	s_addc_u32 s27, s23, -1
	s_and_b64 s[24:25], s[28:29], exec
	s_cselect_b32 s27, s27, s13
	s_cselect_b32 s26, s26, s15
	s_cselect_b32 s25, s63, s60
	s_cselect_b32 s24, s62, s61
	v_lshl_add_u64 v[220:221], s[22:23], 0, v[208:209]
	s_add_i32 m0, s40, 0xc000
	ds_read_b128 v[170:173], v230
	ds_read_b128 v[174:177], v230 offset:1024
	ds_read_b128 v[178:181], v230 offset:2048
	ds_read_b128 v[182:185], v230 offset:3072
	ds_read_b128 v[186:189], v230 offset:4096
	ds_read_b128 v[190:193], v230 offset:5120
	ds_read_b128 v[194:197], v230 offset:6144
	ds_read_b128 v[198:201], v230 offset:7168
	global_load_lds_dwordx4 v[220:221], off
	v_lshl_add_u64 v[220:221], s[22:23], 0, v[210:211]
	s_add_i32 m0, s40, 0xe000
	s_nop 0
	global_load_lds_dwordx4 v[220:221], off
	s_cmp_lg_u32 s64, 0
	s_cbranch_scc1 .Lgw1a_A1
	s_waitcnt vmcnt(24)
	s_branch .Lgw1b_A1

.Lgw1b_A1:
	s_waitcnt lgkmcnt(0)
	s_barrier
	s_setprio 1
	s_waitcnt lgkmcnt(0)
	v_mfma_f32_16x16x32_bf16 v[134:137], v[154:157], v[170:173], v[134:137]
	v_mfma_f32_16x16x32_bf16 v[130:133], v[162:165], v[170:173], v[130:133]
	v_mfma_f32_16x16x32_bf16 v[118:121], v[154:157], v[178:181], v[118:121]
	v_mfma_f32_16x16x32_bf16 v[114:117], v[162:165], v[178:181], v[114:117]
	v_mfma_f32_16x16x32_bf16 v[102:105], v[154:157], v[186:189], v[102:105]
	v_mfma_f32_16x16x32_bf16 v[98:101], v[162:165], v[186:189], v[98:101]
	v_mfma_f32_16x16x32_bf16 v[86:89], v[154:157], v[194:197], v[86:89]
	v_mfma_f32_16x16x32_bf16 v[82:85], v[162:165], v[194:197], v[82:85]
	v_mfma_f32_16x16x32_bf16 v[134:137], v[158:161], v[174:177], v[134:137]
	v_mfma_f32_16x16x32_bf16 v[130:133], v[166:169], v[174:177], v[130:133]
	v_mfma_f32_16x16x32_bf16 v[118:121], v[158:161], v[182:185], v[118:121]
	v_mfma_f32_16x16x32_bf16 v[114:117], v[166:169], v[182:185], v[114:117]
	v_mfma_f32_16x16x32_bf16 v[102:105], v[158:161], v[190:193], v[102:105]
	v_mfma_f32_16x16x32_bf16 v[98:101], v[166:169], v[190:193], v[98:101]
	v_mfma_f32_16x16x32_bf16 v[86:89], v[158:161], v[198:201], v[86:89]
	v_mfma_f32_16x16x32_bf16 v[82:85], v[166:169], v[198:201], v[82:85]
	s_setprio 0
	s_setprio 1
	v_mfma_f32_16x16x32_bf16 v[126:129], v[138:141], v[170:173], v[126:129]
	v_mfma_f32_16x16x32_bf16 v[122:125], v[146:149], v[170:173], v[122:125]
	v_mfma_f32_16x16x32_bf16 v[110:113], v[138:141], v[178:181], v[110:113]
	v_mfma_f32_16x16x32_bf16 v[106:109], v[146:149], v[178:181], v[106:109]
	v_mfma_f32_16x16x32_bf16 v[94:97], v[138:141], v[186:189], v[94:97]
	v_mfma_f32_16x16x32_bf16 v[90:93], v[146:149], v[186:189], v[90:93]
	v_mfma_f32_16x16x32_bf16 v[78:81], v[138:141], v[194:197], v[78:81]
	v_mfma_f32_16x16x32_bf16 v[74:77], v[146:149], v[194:197], v[74:77]
	v_mfma_f32_16x16x32_bf16 v[126:129], v[142:145], v[174:177], v[126:129]
	v_mfma_f32_16x16x32_bf16 v[122:125], v[150:153], v[174:177], v[122:125]
	v_mfma_f32_16x16x32_bf16 v[110:113], v[142:145], v[182:185], v[110:113]
	v_mfma_f32_16x16x32_bf16 v[106:109], v[150:153], v[182:185], v[106:109]
	v_mfma_f32_16x16x32_bf16 v[94:97], v[142:145], v[190:193], v[94:97]
	v_mfma_f32_16x16x32_bf16 v[90:93], v[150:153], v[190:193], v[90:93]
	v_mfma_f32_16x16x32_bf16 v[78:81], v[142:145], v[198:201], v[78:81]
	v_mfma_f32_16x16x32_bf16 v[74:77], v[150:153], v[198:201], v[74:77]
	s_setprio 0
	s_barrier
	ds_read_b128 v[194:197], v230 offset:16384
	ds_read_b128 v[198:201], v230 offset:17408
	ds_read_b128 v[186:189], v230 offset:18432
	ds_read_b128 v[190:193], v230 offset:19456
	ds_read_b128 v[178:181], v230 offset:20480
	ds_read_b128 v[182:185], v230 offset:21504
	ds_read_b128 v[170:173], v230 offset:22528
	ds_read_b128 v[174:177], v230 offset:23552
	s_or_b64 s[28:29], s[20:21], s[28:29]
	s_xor_b64 s[30:31], s[28:29], -1
	s_mov_b64 s[34:35], -1
	s_and_b64 vcc, exec, s[30:31]
	s_cbranch_vccz .LBB0_496
	s_waitcnt vmcnt(2)
	s_mov_b64 s[34:35], 0
.LBB0_496:
	s_andn2_b64 vcc, exec, s[34:35]
	v_lshl_add_u64 v[226:227], s[24:25], 0, v[204:205]
	v_lshl_add_u64 v[224:225], s[24:25], 0, v[2:3]
	v_lshl_add_u64 v[222:223], s[26:27], 0, v[206:207]
	v_lshl_add_u64 v[220:221], s[26:27], 0, v[202:203]
	s_cbranch_vccnz .LBB0_498
	s_mov_b32 m0, s41
	s_add_u32 s34, s24, 0x10000
	global_load_lds_dwordx4 v[226:227], off
	s_mov_b32 m0, s42
	s_addc_u32 s35, s25, 0
	global_load_lds_dwordx4 v[224:225], off
	v_lshl_add_u64 v[244:245], s[34:35], 0, v[204:205]
	s_mov_b32 m0, s43
	s_nop 0
	global_load_lds_dwordx4 v[244:245], off
	v_lshl_add_u64 v[244:245], s[34:35], 0, v[2:3]
	s_mov_b32 m0, s44
	s_nop 0
	global_load_lds_dwordx4 v[244:245], off
	s_mov_b32 m0, s40
	s_nop 0
	global_load_lds_dwordx4 v[222:223], off
	s_mov_b32 m0, s45
	s_nop 0
	global_load_lds_dwordx4 v[220:221], off
	s_cmp_lg_u32 s64, 0
	s_cbranch_scc1 .Lgw2a_A1
	s_cmp_lt_u32 s56, 2
	s_cbranch_scc1 .Lgw2a_A1
	s_waitcnt vmcnt(24)
	s_branch .Lgw2b_A1

.Lgw2b_A1:
.LBB0_498:
	s_waitcnt lgkmcnt(0)
	s_barrier
	s_setprio 1
	s_waitcnt lgkmcnt(0)
	v_mfma_f32_16x16x32_bf16 v[70:73], v[154:157], v[194:197], v[70:73]
	v_mfma_f32_16x16x32_bf16 v[66:69], v[162:165], v[194:197], v[66:69]
	v_mfma_f32_16x16x32_bf16 v[54:57], v[154:157], v[186:189], v[54:57]
	v_mfma_f32_16x16x32_bf16 v[50:53], v[162:165], v[186:189], v[50:53]
	v_mfma_f32_16x16x32_bf16 v[34:37], v[154:157], v[178:181], v[34:37]
	v_mfma_f32_16x16x32_bf16 v[30:33], v[162:165], v[178:181], v[30:33]
	v_mfma_f32_16x16x32_bf16 v[18:21], v[154:157], v[170:173], v[18:21]
	v_mfma_f32_16x16x32_bf16 v[14:17], v[162:165], v[170:173], v[14:17]
	v_mfma_f32_16x16x32_bf16 v[70:73], v[158:161], v[198:201], v[70:73]
	v_mfma_f32_16x16x32_bf16 v[66:69], v[166:169], v[198:201], v[66:69]
	v_mfma_f32_16x16x32_bf16 v[54:57], v[158:161], v[190:193], v[54:57]
	v_mfma_f32_16x16x32_bf16 v[50:53], v[166:169], v[190:193], v[50:53]
	v_mfma_f32_16x16x32_bf16 v[34:37], v[158:161], v[182:185], v[34:37]
	v_mfma_f32_16x16x32_bf16 v[30:33], v[166:169], v[182:185], v[30:33]
	v_mfma_f32_16x16x32_bf16 v[18:21], v[158:161], v[174:177], v[18:21]
	v_mfma_f32_16x16x32_bf16 v[14:17], v[166:169], v[174:177], v[14:17]
	s_setprio 0
	s_setprio 1
	v_mfma_f32_16x16x32_bf16 v[62:65], v[138:141], v[194:197], v[62:65]
	v_mfma_f32_16x16x32_bf16 v[58:61], v[146:149], v[194:197], v[58:61]
	v_mfma_f32_16x16x32_bf16 v[46:49], v[138:141], v[186:189], v[46:49]
	v_mfma_f32_16x16x32_bf16 v[42:45], v[146:149], v[186:189], v[42:45]
	v_mfma_f32_16x16x32_bf16 v[26:29], v[138:141], v[178:181], v[26:29]
	v_mfma_f32_16x16x32_bf16 v[22:25], v[146:149], v[178:181], v[22:25]
	v_mfma_f32_16x16x32_bf16 v[10:13], v[138:141], v[170:173], v[10:13]
	v_mfma_f32_16x16x32_bf16 v[6:9], v[146:149], v[170:173], v[6:9]
	v_mfma_f32_16x16x32_bf16 v[62:65], v[142:145], v[198:201], v[62:65]
	v_mfma_f32_16x16x32_bf16 v[58:61], v[150:153], v[198:201], v[58:61]
	v_mfma_f32_16x16x32_bf16 v[46:49], v[142:145], v[190:193], v[46:49]
	v_mfma_f32_16x16x32_bf16 v[42:45], v[150:153], v[190:193], v[42:45]
	v_mfma_f32_16x16x32_bf16 v[26:29], v[142:145], v[182:185], v[26:29]
	v_mfma_f32_16x16x32_bf16 v[22:25], v[150:153], v[182:185], v[22:25]
	v_mfma_f32_16x16x32_bf16 v[10:13], v[142:145], v[174:177], v[10:13]
	v_mfma_f32_16x16x32_bf16 v[6:9], v[150:153], v[174:177], v[6:9]
	s_setprio 0
	s_barrier
	v_add_u32_e32 v138, 0x18000, v229
	v_add_u32_e32 v150, 0x1c000, v229
	ds_read_b128 v[154:157], v138
	ds_read_b128 v[158:161], v138 offset:1024
	ds_read_b128 v[162:165], v138 offset:2048
	ds_read_b128 v[166:169], v138 offset:3072
	ds_read_b128 v[138:141], v150
	ds_read_b128 v[142:145], v150 offset:1024
	ds_read_b128 v[146:149], v150 offset:2048
	ds_read_b128 v[150:153], v150 offset:3072
	ds_read_b128 v[194:197], v230 offset:32768
	ds_read_b128 v[198:201], v230 offset:33792
	ds_read_b128 v[186:189], v230 offset:34816
	ds_read_b128 v[190:193], v230 offset:35840
	ds_read_b128 v[178:181], v230 offset:36864
	ds_read_b128 v[182:185], v230 offset:37888
	ds_read_b128 v[170:173], v230 offset:38912
	ds_read_b128 v[174:177], v230 offset:39936
	s_mov_b64 s[34:35], -1
	s_and_b64 vcc, exec, s[30:31]
	s_cbranch_vccz .LBB0_500
	s_waitcnt vmcnt(0)
	s_mov_b64 s[34:35], 0

.LBB0_942:
	v_add_u32_e32 v134, 0x10000, v227
	v_add_u32_e32 v146, 0x14000, v227
	ds_read_b128 v[150:153], v134
	ds_read_b128 v[154:157], v134 offset:1024
	ds_read_b128 v[158:161], v134 offset:2048
	ds_read_b128 v[162:165], v134 offset:3072
	ds_read_b128 v[134:137], v146
	ds_read_b128 v[138:141], v146 offset:1024
	ds_read_b128 v[142:145], v146 offset:2048
	ds_read_b128 v[146:149], v146 offset:3072
	s_cmp_lg_u32 s56, s65
	s_cselect_b64 s[28:29], -1, 0
	s_add_u32 s26, s22, 0xfffc0080
	s_addc_u32 s27, s23, -1
	s_and_b64 s[24:25], s[28:29], exec
	s_cselect_b32 s27, s27, s13
	s_cselect_b32 s26, s26, s15
	s_cselect_b32 s25, s64, s61
	s_cselect_b32 s24, s63, s62
	v_lshl_add_u64 v[218:219], s[22:23], 0, v[206:207]
	s_add_i32 m0, s41, 0xc000
	ds_read_b128 v[166:169], v228
	ds_read_b128 v[170:173], v228 offset:1024
	ds_read_b128 v[174:177], v228 offset:2048
	ds_read_b128 v[178:181], v228 offset:3072
	ds_read_b128 v[182:185], v228 offset:4096
	ds_read_b128 v[186:189], v228 offset:5120
	ds_read_b128 v[190:193], v228 offset:6144
	ds_read_b128 v[194:197], v228 offset:7168
	global_load_lds_dwordx4 v[218:219], off
	v_lshl_add_u64 v[218:219], s[22:23], 0, v[208:209]
	s_add_i32 m0, s41, 0xe000
	s_nop 0
	global_load_lds_dwordx4 v[218:219], off
	s_cmp_lg_u32 s65, 0
	s_cbranch_scc1 .Lgw1a_M1
	s_waitcnt vmcnt(24)
	s_branch .Lgw1b_M1

.Lgw1b_M1:
	s_waitcnt lgkmcnt(0)
	s_barrier
	s_setprio 1
	s_waitcnt lgkmcnt(0)
	v_mfma_f32_16x16x32_bf16 v[130:133], v[150:153], v[166:169], v[130:133]
	v_mfma_f32_16x16x32_bf16 v[126:129], v[158:161], v[166:169], v[126:129]
	v_mfma_f32_16x16x32_bf16 v[114:117], v[150:153], v[174:177], v[114:117]
	v_mfma_f32_16x16x32_bf16 v[110:113], v[158:161], v[174:177], v[110:113]
	v_mfma_f32_16x16x32_bf16 v[98:101], v[150:153], v[182:185], v[98:101]
	v_mfma_f32_16x16x32_bf16 v[94:97], v[158:161], v[182:185], v[94:97]
	v_mfma_f32_16x16x32_bf16 v[82:85], v[150:153], v[190:193], v[82:85]
	v_mfma_f32_16x16x32_bf16 v[78:81], v[158:161], v[190:193], v[78:81]
	v_mfma_f32_16x16x32_bf16 v[130:133], v[154:157], v[170:173], v[130:133]
	v_mfma_f32_16x16x32_bf16 v[126:129], v[162:165], v[170:173], v[126:129]
	v_mfma_f32_16x16x32_bf16 v[114:117], v[154:157], v[178:181], v[114:117]
	v_mfma_f32_16x16x32_bf16 v[110:113], v[162:165], v[178:181], v[110:113]
	v_mfma_f32_16x16x32_bf16 v[98:101], v[154:157], v[186:189], v[98:101]
	v_mfma_f32_16x16x32_bf16 v[94:97], v[162:165], v[186:189], v[94:97]
	v_mfma_f32_16x16x32_bf16 v[82:85], v[154:157], v[194:197], v[82:85]
	v_mfma_f32_16x16x32_bf16 v[78:81], v[162:165], v[194:197], v[78:81]
	s_setprio 0
	s_setprio 1
	v_mfma_f32_16x16x32_bf16 v[122:125], v[134:137], v[166:169], v[122:125]
	v_mfma_f32_16x16x32_bf16 v[118:121], v[142:145], v[166:169], v[118:121]
	v_mfma_f32_16x16x32_bf16 v[106:109], v[134:137], v[174:177], v[106:109]
	v_mfma_f32_16x16x32_bf16 v[102:105], v[142:145], v[174:177], v[102:105]
	v_mfma_f32_16x16x32_bf16 v[90:93], v[134:137], v[182:185], v[90:93]
	v_mfma_f32_16x16x32_bf16 v[86:89], v[142:145], v[182:185], v[86:89]
	v_mfma_f32_16x16x32_bf16 v[74:77], v[134:137], v[190:193], v[74:77]
	v_mfma_f32_16x16x32_bf16 v[70:73], v[142:145], v[190:193], v[70:73]
	v_mfma_f32_16x16x32_bf16 v[122:125], v[138:141], v[170:173], v[122:125]
	v_mfma_f32_16x16x32_bf16 v[118:121], v[146:149], v[170:173], v[118:121]
	v_mfma_f32_16x16x32_bf16 v[106:109], v[138:141], v[178:181], v[106:109]
	v_mfma_f32_16x16x32_bf16 v[102:105], v[146:149], v[178:181], v[102:105]
	v_mfma_f32_16x16x32_bf16 v[90:93], v[138:141], v[186:189], v[90:93]
	v_mfma_f32_16x16x32_bf16 v[86:89], v[146:149], v[186:189], v[86:89]
	v_mfma_f32_16x16x32_bf16 v[74:77], v[138:141], v[194:197], v[74:77]
	v_mfma_f32_16x16x32_bf16 v[70:73], v[146:149], v[194:197], v[70:73]
	s_setprio 0
	s_barrier
	ds_read_b128 v[190:193], v228 offset:16384
	ds_read_b128 v[194:197], v228 offset:17408
	ds_read_b128 v[182:185], v228 offset:18432
	ds_read_b128 v[186:189], v228 offset:19456
	ds_read_b128 v[174:177], v228 offset:20480
	ds_read_b128 v[178:181], v228 offset:21504
	ds_read_b128 v[166:169], v228 offset:22528
	ds_read_b128 v[170:173], v228 offset:23552
	s_or_b64 s[28:29], s[20:21], s[28:29]
	s_xor_b64 s[30:31], s[28:29], -1
	s_mov_b64 s[34:35], -1
	s_and_b64 vcc, exec, s[30:31]
	s_cbranch_vccz .LBB0_944
	s_waitcnt vmcnt(2)
	s_mov_b64 s[34:35], 0
.LBB0_944:
	s_andn2_b64 vcc, exec, s[34:35]
	v_lshl_add_u64 v[224:225], s[24:25], 0, v[202:203]
	v_lshl_add_u64 v[222:223], s[24:25], 0, v[198:199]
	v_lshl_add_u64 v[220:221], s[26:27], 0, v[204:205]
	v_lshl_add_u64 v[218:219], s[26:27], 0, v[200:201]
	s_cbranch_vccnz .LBB0_946
	s_mov_b32 m0, s42
	s_add_u32 s34, s24, 0x10000
	global_load_lds_dwordx4 v[224:225], off
	s_mov_b32 m0, s43
	s_addc_u32 s35, s25, 0
	global_load_lds_dwordx4 v[222:223], off
	v_lshl_add_u64 v[244:245], s[34:35], 0, v[202:203]
	s_mov_b32 m0, s44
	s_nop 0
	global_load_lds_dwordx4 v[244:245], off
	v_lshl_add_u64 v[244:245], s[34:35], 0, v[198:199]
	s_mov_b32 m0, s45
	s_nop 0
	global_load_lds_dwordx4 v[244:245], off
	s_mov_b32 m0, s41
	s_nop 0
	global_load_lds_dwordx4 v[220:221], off
	s_mov_b32 m0, s46
	s_nop 0
	global_load_lds_dwordx4 v[218:219], off
	s_cmp_lg_u32 s65, 0
	s_cbranch_scc1 .Lgw2a_M1
	s_cmp_lt_u32 s57, 2
	s_cbranch_scc1 .Lgw2a_M1
	s_waitcnt vmcnt(24)
	s_branch .Lgw2b_M1

.Lgw2b_M1:
.LBB0_946:
	s_waitcnt lgkmcnt(0)
	s_barrier
	s_setprio 1
	s_waitcnt lgkmcnt(0)
	v_mfma_f32_16x16x32_bf16 v[66:69], v[150:153], v[190:193], v[66:69]
	v_mfma_f32_16x16x32_bf16 v[62:65], v[158:161], v[190:193], v[62:65]
	v_mfma_f32_16x16x32_bf16 v[50:53], v[150:153], v[182:185], v[50:53]
	v_mfma_f32_16x16x32_bf16 v[46:49], v[158:161], v[182:185], v[46:49]
	v_mfma_f32_16x16x32_bf16 v[34:37], v[150:153], v[174:177], v[34:37]
	v_mfma_f32_16x16x32_bf16 v[30:33], v[158:161], v[174:177], v[30:33]
	v_mfma_f32_16x16x32_bf16 v[18:21], v[150:153], v[166:169], v[18:21]
	v_mfma_f32_16x16x32_bf16 v[14:17], v[158:161], v[166:169], v[14:17]
	v_mfma_f32_16x16x32_bf16 v[66:69], v[154:157], v[194:197], v[66:69]
	v_mfma_f32_16x16x32_bf16 v[62:65], v[162:165], v[194:197], v[62:65]
	v_mfma_f32_16x16x32_bf16 v[50:53], v[154:157], v[186:189], v[50:53]
	v_mfma_f32_16x16x32_bf16 v[46:49], v[162:165], v[186:189], v[46:49]
	v_mfma_f32_16x16x32_bf16 v[34:37], v[154:157], v[178:181], v[34:37]
	v_mfma_f32_16x16x32_bf16 v[30:33], v[162:165], v[178:181], v[30:33]
	v_mfma_f32_16x16x32_bf16 v[18:21], v[154:157], v[170:173], v[18:21]
	v_mfma_f32_16x16x32_bf16 v[14:17], v[162:165], v[170:173], v[14:17]
	s_setprio 0
	s_setprio 1
	v_mfma_f32_16x16x32_bf16 v[58:61], v[134:137], v[190:193], v[58:61]
	v_mfma_f32_16x16x32_bf16 v[54:57], v[142:145], v[190:193], v[54:57]
	v_mfma_f32_16x16x32_bf16 v[42:45], v[134:137], v[182:185], v[42:45]
	v_mfma_f32_16x16x32_bf16 v[38:41], v[142:145], v[182:185], v[38:41]
	v_mfma_f32_16x16x32_bf16 v[26:29], v[134:137], v[174:177], v[26:29]
	v_mfma_f32_16x16x32_bf16 v[22:25], v[142:145], v[174:177], v[22:25]
	v_mfma_f32_16x16x32_bf16 v[10:13], v[134:137], v[166:169], v[10:13]
	v_mfma_f32_16x16x32_bf16 v[6:9], v[142:145], v[166:169], v[6:9]
	v_mfma_f32_16x16x32_bf16 v[58:61], v[138:141], v[194:197], v[58:61]
	v_mfma_f32_16x16x32_bf16 v[54:57], v[146:149], v[194:197], v[54:57]
	v_mfma_f32_16x16x32_bf16 v[42:45], v[138:141], v[186:189], v[42:45]
	v_mfma_f32_16x16x32_bf16 v[38:41], v[146:149], v[186:189], v[38:41]
	v_mfma_f32_16x16x32_bf16 v[26:29], v[138:141], v[178:181], v[26:29]
	v_mfma_f32_16x16x32_bf16 v[22:25], v[146:149], v[178:181], v[22:25]
	v_mfma_f32_16x16x32_bf16 v[10:13], v[138:141], v[170:173], v[10:13]
	v_mfma_f32_16x16x32_bf16 v[6:9], v[146:149], v[170:173], v[6:9]
	s_setprio 0
	s_barrier
	v_add_u32_e32 v134, 0x18000, v227
	v_add_u32_e32 v146, 0x1c000, v227
	ds_read_b128 v[150:153], v134
	ds_read_b128 v[154:157], v134 offset:1024
	ds_read_b128 v[158:161], v134 offset:2048
	ds_read_b128 v[162:165], v134 offset:3072
	ds_read_b128 v[134:137], v146
	ds_read_b128 v[138:141], v146 offset:1024
	ds_read_b128 v[142:145], v146 offset:2048
	ds_read_b128 v[146:149], v146 offset:3072
	ds_read_b128 v[190:193], v228 offset:32768
	ds_read_b128 v[194:197], v228 offset:33792
	ds_read_b128 v[182:185], v228 offset:34816
	ds_read_b128 v[186:189], v228 offset:35840
	ds_read_b128 v[174:177], v228 offset:36864
	ds_read_b128 v[178:181], v228 offset:37888
	ds_read_b128 v[166:169], v228 offset:38912
	ds_read_b128 v[170:173], v228 offset:39936
	s_mov_b64 s[34:35], -1
	s_and_b64 vcc, exec, s[30:31]
	s_cbranch_vccz .LBB0_948
	s_waitcnt vmcnt(0)
	s_mov_b64 s[34:35], 0
